# speedup vs baseline: 1.1020x; 1.0073x over previous
; #define EPI_LOOP(MODE) do { _Pragma("unroll") for (int m = 0; m < 8; ++m) _Pragma("unroll") for (int n = 0; n < 4; ++n) \
;         epi_store<MODE>(g, brow + wr * 128 + m * 16 + fr, bcol + wc * 64 + n * 16 + fq * 4, acc[m][n]); } while (0)
; template <int MODE> __device__ __forceinline__ void epi_store(const GemmDesc& g, int row, int col, f32x4 v) {
;     ...
;     case E_RESID: {
;       const float4 xv = *(const float4*)(g.xs + (size_t)row * DM + col);
;       *(float4*)((float*)g.o0 + (size_t)row * DM + col) = make_float4(xv.x + v[0], xv.y + v[1], xv.z + v[2], xv.w + v[3]);
;     } break;
; __device__ __forceinline__ void gemm_run(const GemmDesc& g, char* shm) {
;     ...
;     switch (g.emode) {
;       case E_SQRELU: EPI_LOOP(E_SQRELU); break;
;       case E_RESID: EPI_LOOP(E_RESID); break;
.LBB0_1035:
	s_andn2_b64 vcc, exec, s[4:5]
	s_cbranch_vccnz .LBB0_261
	v_and_b32_e32 v152, 63, v135
	v_lshrrev_b32_e32 v153, 3, v152
	v_and_b32_e32 v154, 7, v152
	v_lshrrev_b32_e32 v155, 8, v135
	v_bfe_u32 v156, v135, 6, 2
	v_lshrrev_b32_e32 v157, 6, v135
	v_lshl_add_u32 v128, v155, 7, v153
	v_add_u32_e32 v128, s39, v128
	v_lshlrev_b32_e32 v130, 2, v154
	v_lshl_add_u32 v129, v156, 6, v130
	v_add_u32_e32 v129, s38, v129
	v_lshlrev_b32_e32 v129, 2, v129
	v_lshl_add_u32 v144, v128, 12, v129
	v_add_u32_e32 v145, 0x8000, v144
	v_mov_b32_e32 v146, v144
	v_mov_b32_e32 v147, v145
	v_and_b32_e32 v128, 15, v152
	v_lshrrev_b32_e32 v129, 4, v152
	v_and_b32_e32 v130, 7, v128
	v_xor_b32_e32 v129, v129, v130
	v_lshlrev_b32_e32 v129, 4, v129
	v_lshl_add_u32 v129, v128, 7, v129
	v_lshl_add_u32 v129, v157, 11, v129
	v_add_u32_e32 v148, 0x20000, v129
	v_xor_b32_e32 v149, 64, v148
	v_xor_b32_e32 v130, v154, v153
	v_lshlrev_b32_e32 v130, 4, v130
	v_lshl_add_u32 v130, v153, 7, v130
	v_lshl_add_u32 v130, v157, 11, v130
	v_add_u32_e32 v150, 0x20000, v130
	global_load_dwordx4 v[204:207], v144, s[20:21]
	global_load_dwordx4 v[208:211], v145, s[20:21]
	global_load_dwordx4 v[212:215], v144, s[20:21] offset:128
	global_load_dwordx4 v[216:219], v145, s[20:21] offset:128
	v_add_u32_e32 v144, 0x10000, v144
	v_add_u32_e32 v145, 0x10000, v145
	global_load_dwordx4 v[220:223], v144, s[20:21]
	global_load_dwordx4 v[224:227], v145, s[20:21]
	ds_write_b128 v148, v[124:127]
	ds_write_b128 v149, v[120:123]
	ds_read_b128 v[236:239], v150
	ds_read_b128 v[240:243], v150 offset:1024
	global_load_dwordx4 v[228:231], v144, s[20:21] offset:128
	global_load_dwordx4 v[232:235], v145, s[20:21] offset:128
	v_add_u32_e32 v144, 0x10000, v144
	v_add_u32_e32 v145, 0x10000, v145
	s_waitcnt vmcnt(6)
	s_waitcnt lgkmcnt(0)
	v_pk_add_f32 v[236:237], v[236:237], v[204:205]
	v_pk_add_f32 v[238:239], v[238:239], v[206:207]
	v_pk_add_f32 v[240:241], v[240:241], v[208:209]
	v_pk_add_f32 v[242:243], v[242:243], v[210:211]
	global_store_dwordx4 v146, v[236:239], s[66:67]
	global_store_dwordx4 v147, v[240:243], s[66:67]
	ds_write_b128 v148, v[116:119]
	ds_write_b128 v149, v[112:115]
	ds_read_b128 v[128:131], v150
	ds_read_b128 v[152:155], v150 offset:1024
	global_load_dwordx4 v[204:207], v144, s[20:21]
	global_load_dwordx4 v[208:211], v145, s[20:21]
	s_waitcnt vmcnt(8)
	s_waitcnt lgkmcnt(0)
	v_pk_add_f32 v[128:129], v[128:129], v[212:213]
	v_pk_add_f32 v[130:131], v[130:131], v[214:215]
	v_pk_add_f32 v[152:153], v[152:153], v[216:217]
	v_pk_add_f32 v[154:155], v[154:155], v[218:219]
	global_store_dwordx4 v146, v[128:131], s[66:67] offset:128
	global_store_dwordx4 v147, v[152:155], s[66:67] offset:128
	v_add_u32_e32 v146, 0x10000, v146
	v_add_u32_e32 v147, 0x10000, v147
	ds_write_b128 v148, v[108:111]
	ds_write_b128 v149, v[104:107]
	ds_read_b128 v[236:239], v150
	ds_read_b128 v[240:243], v150 offset:1024
	global_load_dwordx4 v[212:215], v144, s[20:21] offset:128
	global_load_dwordx4 v[216:219], v145, s[20:21] offset:128
	v_add_u32_e32 v144, 0x10000, v144
	v_add_u32_e32 v145, 0x10000, v145
	s_waitcnt vmcnt(10)
	s_waitcnt lgkmcnt(0)
	v_pk_add_f32 v[236:237], v[236:237], v[220:221]
	v_pk_add_f32 v[238:239], v[238:239], v[222:223]
	v_pk_add_f32 v[240:241], v[240:241], v[224:225]
	v_pk_add_f32 v[242:243], v[242:243], v[226:227]
	global_store_dwordx4 v146, v[236:239], s[66:67]
	global_store_dwordx4 v147, v[240:243], s[66:67]
	ds_write_b128 v148, v[100:103]
	ds_write_b128 v149, v[96:99]
	ds_read_b128 v[128:131], v150
	ds_read_b128 v[152:155], v150 offset:1024
	global_load_dwordx4 v[220:223], v144, s[20:21]
	global_load_dwordx4 v[224:227], v145, s[20:21]
	s_waitcnt vmcnt(12)
	s_waitcnt lgkmcnt(0)
	v_pk_add_f32 v[128:129], v[128:129], v[228:229]
	v_pk_add_f32 v[130:131], v[130:131], v[230:231]
	v_pk_add_f32 v[152:153], v[152:153], v[232:233]
	v_pk_add_f32 v[154:155], v[154:155], v[234:235]
	global_store_dwordx4 v146, v[128:131], s[66:67] offset:128
	global_store_dwordx4 v147, v[152:155], s[66:67] offset:128
	v_add_u32_e32 v146, 0x10000, v146
	v_add_u32_e32 v147, 0x10000, v147
	ds_write_b128 v148, v[92:95]
	ds_write_b128 v149, v[88:91]
	ds_read_b128 v[236:239], v150
	ds_read_b128 v[240:243], v150 offset:1024
	global_load_dwordx4 v[228:231], v144, s[20:21] offset:128
	global_load_dwordx4 v[232:235], v145, s[20:21] offset:128
	v_add_u32_e32 v144, 0x10000, v144
	v_add_u32_e32 v145, 0x10000, v145
	s_waitcnt vmcnt(12)
	s_waitcnt lgkmcnt(0)
	v_pk_add_f32 v[236:237], v[236:237], v[204:205]
	v_pk_add_f32 v[238:239], v[238:239], v[206:207]
	v_pk_add_f32 v[240:241], v[240:241], v[208:209]
	v_pk_add_f32 v[242:243], v[242:243], v[210:211]
	global_store_dwordx4 v146, v[236:239], s[66:67]
	global_store_dwordx4 v147, v[240:243], s[66:67]
	ds_write_b128 v148, v[84:87]
	ds_write_b128 v149, v[80:83]
	ds_read_b128 v[128:131], v150
	ds_read_b128 v[152:155], v150 offset:1024
	global_load_dwordx4 v[204:207], v144, s[20:21]
	global_load_dwordx4 v[208:211], v145, s[20:21]
	s_waitcnt vmcnt(12)
	s_waitcnt lgkmcnt(0)
	v_pk_add_f32 v[128:129], v[128:129], v[212:213]
	v_pk_add_f32 v[130:131], v[130:131], v[214:215]
	v_pk_add_f32 v[152:153], v[152:153], v[216:217]
	v_pk_add_f32 v[154:155], v[154:155], v[218:219]
	global_store_dwordx4 v146, v[128:131], s[66:67] offset:128
	global_store_dwordx4 v147, v[152:155], s[66:67] offset:128
	v_add_u32_e32 v146, 0x10000, v146
	v_add_u32_e32 v147, 0x10000, v147
	ds_write_b128 v148, v[76:79]
	ds_write_b128 v149, v[72:75]
	ds_read_b128 v[236:239], v150
	ds_read_b128 v[240:243], v150 offset:1024
	global_load_dwordx4 v[212:215], v144, s[20:21] offset:128
	global_load_dwordx4 v[216:219], v145, s[20:21] offset:128
	v_add_u32_e32 v144, 0x10000, v144
	v_add_u32_e32 v145, 0x10000, v145
	s_waitcnt vmcnt(12)
; #define EPI_LOOP(MODE) do { _Pragma("unroll") for (int m = 0; m < 8; ++m) _Pragma("unroll") for (int n = 0; n < 4; ++n) \
;         epi_store<MODE>(g, brow + wr * 128 + m * 16 + fr, bcol + wc * 64 + n * 16 + fq * 4, acc[m][n]); } while (0)
; template <int MODE> __device__ __forceinline__ void epi_store(const GemmDesc& g, int row, int col, f32x4 v) {
;     ...
;     case E_RESID: {
;       const float4 xv = *(const float4*)(g.xs + (size_t)row * DM + col);
;       *(float4*)((float*)g.o0 + (size_t)row * DM + col) = make_float4(xv.x + v[0], xv.y + v[1], xv.z + v[2], xv.w + v[3]);
;     } break;
; __device__ __forceinline__ void gemm_run(const GemmDesc& g, char* shm) {
;     ...
;     switch (g.emode) {
;       case E_SQRELU: EPI_LOOP(E_SQRELU); break;
;       case E_RESID: EPI_LOOP(E_RESID); break;
	s_waitcnt lgkmcnt(0)
	v_pk_add_f32 v[236:237], v[236:237], v[220:221]
	v_pk_add_f32 v[238:239], v[238:239], v[222:223]
	v_pk_add_f32 v[240:241], v[240:241], v[224:225]
	v_pk_add_f32 v[242:243], v[242:243], v[226:227]
	global_store_dwordx4 v146, v[236:239], s[66:67]
	global_store_dwordx4 v147, v[240:243], s[66:67]
	ds_write_b128 v148, v[68:71]
	ds_write_b128 v149, v[64:67]
	ds_read_b128 v[128:131], v150
	ds_read_b128 v[152:155], v150 offset:1024
	global_load_dwordx4 v[220:223], v144, s[20:21]
	global_load_dwordx4 v[224:227], v145, s[20:21]
	s_waitcnt vmcnt(12)
	s_waitcnt lgkmcnt(0)
	v_pk_add_f32 v[128:129], v[128:129], v[228:229]
	v_pk_add_f32 v[130:131], v[130:131], v[230:231]
	v_pk_add_f32 v[152:153], v[152:153], v[232:233]
	v_pk_add_f32 v[154:155], v[154:155], v[234:235]
	global_store_dwordx4 v146, v[128:131], s[66:67] offset:128
	global_store_dwordx4 v147, v[152:155], s[66:67] offset:128
	v_add_u32_e32 v146, 0x10000, v146
	v_add_u32_e32 v147, 0x10000, v147
	ds_write_b128 v148, v[60:63]
	ds_write_b128 v149, v[56:59]
	ds_read_b128 v[236:239], v150
	ds_read_b128 v[240:243], v150 offset:1024
	global_load_dwordx4 v[228:231], v144, s[20:21] offset:128
	global_load_dwordx4 v[232:235], v145, s[20:21] offset:128
	v_add_u32_e32 v144, 0x10000, v144
	v_add_u32_e32 v145, 0x10000, v145
	s_waitcnt vmcnt(12)
	s_waitcnt lgkmcnt(0)
	v_pk_add_f32 v[236:237], v[236:237], v[204:205]
	v_pk_add_f32 v[238:239], v[238:239], v[206:207]
	v_pk_add_f32 v[240:241], v[240:241], v[208:209]
	v_pk_add_f32 v[242:243], v[242:243], v[210:211]
	global_store_dwordx4 v146, v[236:239], s[66:67]
	global_store_dwordx4 v147, v[240:243], s[66:67]
	ds_write_b128 v148, v[52:55]
	ds_write_b128 v149, v[48:51]
	ds_read_b128 v[128:131], v150
	ds_read_b128 v[152:155], v150 offset:1024
	global_load_dwordx4 v[204:207], v144, s[20:21]
	global_load_dwordx4 v[208:211], v145, s[20:21]
	s_waitcnt vmcnt(12)
	s_waitcnt lgkmcnt(0)
	v_pk_add_f32 v[128:129], v[128:129], v[212:213]
	v_pk_add_f32 v[130:131], v[130:131], v[214:215]
	v_pk_add_f32 v[152:153], v[152:153], v[216:217]
	v_pk_add_f32 v[154:155], v[154:155], v[218:219]
	global_store_dwordx4 v146, v[128:131], s[66:67] offset:128
	global_store_dwordx4 v147, v[152:155], s[66:67] offset:128
	v_add_u32_e32 v146, 0x10000, v146
	v_add_u32_e32 v147, 0x10000, v147
	ds_write_b128 v148, v[44:47]
	ds_write_b128 v149, v[40:43]
	ds_read_b128 v[236:239], v150
	ds_read_b128 v[240:243], v150 offset:1024
	global_load_dwordx4 v[212:215], v144, s[20:21] offset:128
	global_load_dwordx4 v[216:219], v145, s[20:21] offset:128
	v_add_u32_e32 v144, 0x10000, v144
	v_add_u32_e32 v145, 0x10000, v145
	s_waitcnt vmcnt(12)
	s_waitcnt lgkmcnt(0)
	v_pk_add_f32 v[236:237], v[236:237], v[220:221]
	v_pk_add_f32 v[238:239], v[238:239], v[222:223]
	v_pk_add_f32 v[240:241], v[240:241], v[224:225]
	v_pk_add_f32 v[242:243], v[242:243], v[226:227]
	global_store_dwordx4 v146, v[236:239], s[66:67]
	global_store_dwordx4 v147, v[240:243], s[66:67]
	ds_write_b128 v148, v[36:39]
	ds_write_b128 v149, v[32:35]
	ds_read_b128 v[128:131], v150
	ds_read_b128 v[152:155], v150 offset:1024
	global_load_dwordx4 v[220:223], v144, s[20:21]
	global_load_dwordx4 v[224:227], v145, s[20:21]
	s_waitcnt vmcnt(12)
	s_waitcnt lgkmcnt(0)
	v_pk_add_f32 v[128:129], v[128:129], v[228:229]
	v_pk_add_f32 v[130:131], v[130:131], v[230:231]
	v_pk_add_f32 v[152:153], v[152:153], v[232:233]
	v_pk_add_f32 v[154:155], v[154:155], v[234:235]
	global_store_dwordx4 v146, v[128:131], s[66:67] offset:128
	global_store_dwordx4 v147, v[152:155], s[66:67] offset:128
	v_add_u32_e32 v146, 0x10000, v146
	v_add_u32_e32 v147, 0x10000, v147
	ds_write_b128 v148, v[28:31]
	ds_write_b128 v149, v[24:27]
	ds_read_b128 v[236:239], v150
	ds_read_b128 v[240:243], v150 offset:1024
	global_load_dwordx4 v[228:231], v144, s[20:21] offset:128
	global_load_dwordx4 v[232:235], v145, s[20:21] offset:128
	v_add_u32_e32 v144, 0x10000, v144
	v_add_u32_e32 v145, 0x10000, v145
	s_waitcnt vmcnt(12)
	s_waitcnt lgkmcnt(0)
	v_pk_add_f32 v[236:237], v[236:237], v[204:205]
	v_pk_add_f32 v[238:239], v[238:239], v[206:207]
	v_pk_add_f32 v[240:241], v[240:241], v[208:209]
	v_pk_add_f32 v[242:243], v[242:243], v[210:211]
	global_store_dwordx4 v146, v[236:239], s[66:67]
	global_store_dwordx4 v147, v[240:243], s[66:67]
	ds_write_b128 v148, v[20:23]
	ds_write_b128 v149, v[16:19]
	ds_read_b128 v[128:131], v150
	ds_read_b128 v[152:155], v150 offset:1024
	s_waitcnt vmcnt(10)
	s_waitcnt lgkmcnt(0)
	v_pk_add_f32 v[128:129], v[128:129], v[212:213]
	v_pk_add_f32 v[130:131], v[130:131], v[214:215]
	v_pk_add_f32 v[152:153], v[152:153], v[216:217]
	v_pk_add_f32 v[154:155], v[154:155], v[218:219]
	global_store_dwordx4 v146, v[128:131], s[66:67] offset:128
	global_store_dwordx4 v147, v[152:155], s[66:67] offset:128
	v_add_u32_e32 v146, 0x10000, v146
	v_add_u32_e32 v147, 0x10000, v147
	ds_write_b128 v148, v[12:15]
	ds_write_b128 v149, v[8:11]
	ds_read_b128 v[236:239], v150
	ds_read_b128 v[240:243], v150 offset:1024
	s_waitcnt vmcnt(8)
	s_waitcnt lgkmcnt(0)
	v_pk_add_f32 v[236:237], v[236:237], v[220:221]
	v_pk_add_f32 v[238:239], v[238:239], v[222:223]
	v_pk_add_f32 v[240:241], v[240:241], v[224:225]
	v_pk_add_f32 v[242:243], v[242:243], v[226:227]
	global_store_dwordx4 v146, v[236:239], s[66:67]
	global_store_dwordx4 v147, v[240:243], s[66:67]
	ds_write_b128 v148, v[4:7]
	ds_write_b128 v149, v[0:3]
	ds_read_b128 v[128:131], v150
	ds_read_b128 v[152:155], v150 offset:1024
	s_waitcnt vmcnt(6)
	s_waitcnt lgkmcnt(0)
	v_pk_add_f32 v[128:129], v[128:129], v[228:229]
	v_pk_add_f32 v[130:131], v[130:131], v[230:231]
	v_pk_add_f32 v[152:153], v[152:153], v[232:233]
	v_pk_add_f32 v[154:155], v[154:155], v[234:235]
	global_store_dwordx4 v146, v[128:131], s[66:67] offset:128
	global_store_dwordx4 v147, v[152:155], s[66:67] offset:128
	s_branch .LBB0_261
